# GEMM phases: one static s_setprio 1 for waves 4-7 (the lagging half of the role-split K-loop), reset to 0 at the phase loop header
# baseline (speedup 1.0000x reference)
;     __device__ bool next(int i, Unit& u) const {
;         const long L = (long)i * G + c;
;         if (L >= nwg) { const long j = L - nwg; if (j >= (long)nM2 * nN * nsplit) return false;
;             const int jj = (int)j; u.ks = jj % nsplit; const int tl = jj / nsplit; u.pn = tl % nN; u.pm = nM + tl / nN; return true; }
;         u.ks = -1;
;         int wgid = (int)L; { const int q = nwg / NXCD, r = nwg % NXCD, xcd = wgid % NXCD, off = wgid / NXCD; wgid = (xcd < r ? xcd * (q + 1) : r * (q + 1) + (xcd - r) * q) + off; }
;         const int nig = WGM * nN, gid = wgid / nig, fm = gid * WGM, gsz = (nM - fm) < WGM ? (nM - fm) : WGM;
;         u.pm = fm + ((wgid % nig) % gsz); u.pn = (wgid % nig) / gsz; return true;
.LBB0_76:
	v_readfirstlane_b32 s14, v208
	s_nop 3
	s_bitcmp1_b32 s14, 8
	s_cbranch_scc0 .Lgprio_1
	s_setprio 1
.Lgprio_1:
	s_cmpk_lt_i32 s51, 0x100
	s_mov_b64 s[12:13], -1
	s_cbranch_scc1 .LBB0_79
	s_and_b32 s0, s51, 0x7fffff00
	s_cmpk_eq_i32 s0, 0x100
	v_readlane_b32 s16, v249, 57
	s_cselect_b64 s[0:1], -1, 0
	v_readlane_b32 s17, v249, 58
	s_and_b64 s[0:1], s[16:17], s[0:1]
	s_mov_b64 s[12:13], 0
	s_andn2_b64 vcc, exec, s[0:1]
	s_mov_b64 s[0:1], 0
	s_cbranch_vccnz .LBB0_79
	s_and_b32 s0, s51, 0xff
	s_lshr_b32 s0, s0, s72
	s_and_b32 s26, s0, 7
	s_lshr_b32 s0, s0, 3
	s_or_b32 s0, s0, 32
	s_and_b32 s36, s73, s51
	s_and_b32 s28, s0, 63
	s_mov_b64 s[0:1], -1

; #define PG8_WAIT_V(n) asm volatile("s_waitcnt vmcnt(" #n ")" ::: "memory")
; #define PG8_BAR __builtin_amdgcn_s_barrier()
; template <class Epi, bool ALIGN_EPI>
; __device__ __forceinline__ void gemm_phase(LAS unsigned char* lds, const int tid, const Gemm g, const StaticOrder& S, const Epi& E) {
;     const int wid = __builtin_amdgcn_readfirstlane(tid >> 6), lane = tid & 63, wr = wid >> 2, wc = wid & 3, fr = lane & 15, fq = lane >> 4;
;     const int K = g.K, nt_full = K / BK, nt_split = S.nsplit > 0 ? nt_full / S.nsplit : nt_full;
;     const unsigned rsA = g.rowsA > 0 ? 128u : (unsigned)K * 2u, rsB = g.rowsB > 0 ? 128u : (unsigned)K * 2u;
;     const size_t kstepA = g.rowsA > 0 ? (size_t)g.rowsA * 128 : (size_t)(BK * 2), kstepB = g.rowsB > 0 ? (size_t)g.rowsB * 128 : (size_t)(BK * 2);
;     unsigned voffA[2], voffB[2];
; #pragma unroll
;     for (int i = 0; i < 2; ++i) { int R, C; stage_rc(tid * 16 + i * 8192, R, C); const int Rb = Epi::PERM ? ((R & ~31) + perm32(R & 31)) : R;
;         voffA[i] = (unsigned)R * rsA + (unsigned)C * 2u; voffB[i] = (unsigned)Rb * rsB + (unsigned)C * 2u; }
;     const size_t hstepA = (size_t)HALF * rsA, hstepB = (size_t)HALF * rsB;
;     const size_t tstepA = 2 * hstepA, tstepB = 2 * hstepB;
;     const unsigned ldsw = (unsigned)wid * 1024u;
;     const int aoff = lds_byte(wr * 64 + fr, fq * 8), boff = lds_byte(wc * 32 + fr, fq * 8);
;     ...
;     Unit cur, nxt; int ui = 0;
;     if (!S.next(0, cur)) return;
;     f32x4 acc[2][2][4][2];
; #pragma unroll
;     for (int a = 0; a < 2; ++a)
; #pragma unroll
;         for (int b = 0; b < 2; ++b)
; #pragma unroll
;             for (int m = 0; m < 4; ++m)
; #pragma unroll
;                 for (int n = 0; n < 2; ++n) acc[a][b][m][n] = (f32x4){0.f, 0.f, 0.f, 0.f};
;     bf16x8 At[4][2], B0[2][2], B1[2][2];
;     ...
;     const char* cA = (const char*)g.A + (size_t)cur.pm * tstepA + PG8_KOFFA(cur); const char* cB = (const char*)g.Bt + (size_t)cur.pn * tstepB + PG8_KOFFB(cur);
;     PG8_STAGE(PG8_SB(0, 0), cB, voffB); PG8_STAGE(PG8_SB(0, 1), cB + hstepB, voffB); PG8_STAGE(PG8_SA(0, 0), cA, voffA); PG8_STAGE(PG8_SA(0, 1), cA + hstepA, voffA);
;     if (wr == 1) PG8_BAR;
;     PG8_WAIT_V(2); PG8_BAR;
;     PG8_STAGE(PG8_SB(1, 0), cB + kstepB, voffB); PG8_STAGE(PG8_SA(1, 0), cA + kstepA, voffA); PG8_STAGE(PG8_SB(1, 1), cB + hstepB + kstepB, voffB);
;     PG8_WAIT_V(6); PG8_BAR;
.LBB0_133:
	s_andn2_b64 vcc, exec, s[0:1]
	s_cbranch_vccnz .LBB0_150
	v_readfirstlane_b32 s12, v208
	s_nop 3
	s_bitcmp1_b32 s12, 8
	s_cbranch_scc0 .Lgprio_2
	s_setprio 1
.Lgprio_2:
	s_lshr_b32 s36, s62, 3
	s_cmp_ge_i32 s51, s36
	v_readfirstlane_b32 s12, v208
	s_cbranch_scc1 .LBB0_150
	v_lshlrev_b32_e32 v0, 4, v208
	v_add_u32_e32 v2, 0x2000, v0
	v_ashrrev_i32_e32 v3, 31, v2
	v_lshrrev_b32_e32 v3, 22, v3
	v_add_u32_e32 v3, v2, v3
	v_ashrrev_i32_e32 v10, 10, v3
	v_mul_i32_i24_e32 v3, 0x400, v10
	v_sub_u32_e32 v2, v2, v3
	v_lshrrev_b32_e32 v3, 4, v2
	v_bitop3_b32 v2, v3, v2, 32 bitop3:0x6c
	v_ashrrev_i32_e32 v3, 31, v2
	v_lshrrev_b32_e32 v3, 26, v3
	s_ashr_i32 s1, s12, 6
	v_add_u32_e32 v3, v2, v3
	v_lshlrev_b32_e32 v4, 3, v10
	s_ashr_i32 s13, s12, 8
	s_lshl_b32 s30, s1, 10
	v_readlane_b32 s0, v249, 59
	v_ashrrev_i32_e32 v11, 6, v3
	v_and_b32_e32 v4, -16, v4
	s_add_u32 s31, s0, 0x4100000
	v_readlane_b32 s0, v249, 60
	v_add_u32_e32 v4, v11, v4
	s_addc_u32 s34, s0, 0
	v_and_b32_e32 v5, 3, v11
	s_mov_b32 s0, 0xfffe0
	v_lshrrev_b32_e32 v6, 2, v4
	v_lshlrev_b32_e32 v7, 1, v4
	v_and_b32_e32 v3, 0xc0, v3
	v_and_or_b32 v5, v4, s0, v5
	v_and_b32_e32 v6, 4, v6
	v_and_b32_e32 v7, 24, v7
	v_sub_u32_e32 v2, v2, v3
	v_or3_b32 v5, v5, v6, v7
	v_lshlrev_b32_e32 v6, 5, v10
	v_ashrrev_i16_sdwa v2, v226, sext(v2) dst_sel:DWORD dst_unused:UNUSED_PAD src0_sel:DWORD src1_sel:BYTE_0
	v_and_b32_e32 v6, 32, v6
	v_bfe_i32 v12, v2, 0, 16
	v_add_lshl_u32 v2, v6, v12, 1
	v_lshl_add_u32 v130, v5, 12, v2
	v_lshl_add_u32 v132, v4, 12, v2
	v_bfe_i32 v2, v208, 27, 1
	v_lshrrev_b32_e32 v2, 22, v2
	v_add_u32_e32 v2, v0, v2
	v_and_b32_e32 v2, 0xfffffc00, v2
	v_sub_u32_e32 v0, v0, v2
	v_lshrrev_b32_e32 v2, 4, v0
	v_ashrrev_i32_e32 v3, 31, v208
	v_bitop3_b32 v0, v2, v0, 32 bitop3:0x6c
	v_lshrrev_b32_e32 v3, 26, v3
	v_ashrrev_i32_e32 v2, 31, v0
	v_add_u32_e32 v3, v208, v3
	v_lshrrev_b32_e32 v2, 26, v2
	v_ashrrev_i32_e32 v14, 6, v3
	v_add_u32_e32 v2, v0, v2
	v_lshlrev_b32_e32 v3, 3, v14
	v_ashrrev_i32_e32 v13, 6, v2
	v_and_b32_e32 v3, -16, v3
	v_add_u32_e32 v3, v13, v3
	v_and_b32_e32 v4, 3, v13
	s_ashr_i32 s47, s51, 31
	v_and_or_b32 v4, v3, s0, v4
	s_lshr_b32 s0, s47, 29
	s_add_i32 s0, s51, s0
	s_ashr_i32 s10, s0, 3
	s_and_b32 s0, s0, -8
	s_sub_i32 s0, s51, s0
	s_lshr_b32 s41, s62, 6
	s_lshr_b32 s11, s0, 31
	s_or_b32 s11, s41, s11
	s_mul_i32 s0, s0, s11
	s_add_i32 s0, s0, s10
	s_ashr_i32 s10, s0, 31
	s_lshr_b32 s10, s10, 24
	s_add_i32 s10, s0, s10
	v_lshrrev_b32_e32 v5, 2, v3
	v_lshlrev_b32_e32 v6, 1, v3
	v_and_b32_e32 v2, 0xc0, v2
	s_ashr_i32 s11, s10, 8
	s_lshr_b32 s35, s62, 8
	v_and_b32_e32 v5, 4, v5
	v_and_b32_e32 v6, 24, v6
	v_sub_u32_e32 v0, v0, v2
	s_lshl_b32 s14, s11, 3
	v_or3_b32 v4, v4, v5, v6
	v_lshlrev_b32_e32 v5, 5, v14
	v_ashrrev_i16_sdwa v0, v226, sext(v0) dst_sel:DWORD dst_unused:UNUSED_PAD src0_sel:DWORD src1_sel:BYTE_0
	s_sub_i32 s11, s35, s14
	v_and_b32_e32 v5, 32, v5
	v_bfe_i32 v15, v0, 0, 16
	s_min_u32 s15, s11, 8
	s_and_b32 s10, s10, 0xffffff00
	v_add_lshl_u32 v2, v5, v15, 1
	s_sub_i32 s16, s0, s10
	v_cvt_f32_ubyte0_e32 v5, s15
	v_lshl_add_u32 v0, v4, 12, v2
	v_cvt_f32_i32_e32 v4, s16
	v_rcp_iflag_f32_e32 v6, v5
	v_lshl_add_u32 v134, v3, 12, v2
	s_ashr_i32 s0, s16, 30
	s_or_b32 s0, s0, 1
	v_mul_f32_e32 v2, v4, v6
	v_trunc_f32_e32 v2, v2
	v_fma_f32 v3, -v2, v5, v4
	v_cvt_i32_f32_e32 v2, v2
	v_cmp_ge_f32_e64 s[10:11], |v3|, v5
	s_and_b64 s[10:11], s[10:11], exec
	s_cselect_b32 s0, s0, 0
	v_readfirstlane_b32 s10, v2
	s_add_i32 s0, s10, s0
	s_mul_i32 s10, s0, s15
	s_sub_i32 s10, s16, s10
	s_sext_i32_i16 s10, s10
	s_add_i32 s22, s14, s10
	s_ashr_i32 s23, s22, 31
	s_lshl_b64 s[10:11], s[22:23], 20
	v_readlane_b32 s14, v248, 4
	s_add_u32 s24, s14, s10
	v_readlane_b32 s10, v249, 63
	s_addc_u32 s25, s10, s11
	s_bfe_i64 s[10:11], s[0:1], 0x100000
	s_lshl_b64 s[10:11], s[10:11], 20
	s_add_u32 s26, s31, s10
	s_addc_u32 s27, s34, s11
	s_add_i32 s23, s30, 0
	s_add_i32 m0, s23, 0x10000
	v_mov_b32_e32 v131, v1
	global_load_lds_dwordx4 v0, s[26:27]
	s_add_i32 m0, s23, 0x12000
	s_add_u32 s10, s26, 0x80000
	global_load_lds_dwordx4 v130, s[26:27]
	s_addc_u32 s11, s27, 0
	s_add_i32 m0, s23, 0x14000
	s_add_i32 s52, s23, 0x2000
	global_load_lds_dwordx4 v0, s[10:11]
	s_add_i32 m0, s23, 0x16000
	v_mov_b32_e32 v135, v1
	global_load_lds_dwordx4 v130, s[10:11]
	s_mov_b32 m0, s23
	s_add_u32 s10, s24, 0x80000
	global_load_lds_dwordx4 v134, s[24:25]
	s_mov_b32 m0, s52
	s_addc_u32 s11, s25, 0
	s_add_i32 s54, s23, 0x4000
	global_load_lds_dwordx4 v132, s[24:25]
	s_mov_b32 m0, s54
	s_add_i32 s55, s23, 0x6000
	global_load_lds_dwordx4 v134, s[10:11]
	s_mov_b32 m0, s55
	v_mov_b32_e32 v133, v1
	global_load_lds_dwordx4 v132, s[10:11]
	s_cmp_eq_u32 s13, 1
	s_mov_b32 s71, s56
	v_lshl_add_u64 v[8:9], s[26:27], 0, v[0:1]
	v_lshl_add_u64 v[6:7], s[26:27], 0, v[130:131]
	v_lshl_add_u64 v[2:3], s[24:25], 0, v[134:135]
	s_cselect_b64 s[10:11], -1, 0
	s_cmp_lg_u32 s13, 1
	v_lshl_add_u64 v[4:5], s[24:25], 0, v[132:133]
	s_cbranch_scc1 .LBB0_137
	s_barrier

;     __device__ bool next(int i, Unit& u) const {
;         const long L = (long)i * G + c;
;         if (L >= nwg) { const long j = L - nwg; if (j >= (long)nM2 * nN * nsplit) return false;
;             const int jj = (int)j; u.ks = jj % nsplit; const int tl = jj / nsplit; u.pn = tl % nN; u.pm = nM + tl / nN; return true; }
;         u.ks = -1;
;         int wgid = (int)L; { const int q = nwg / NXCD, r = nwg % NXCD, xcd = wgid % NXCD, off = wgid / NXCD; wgid = (xcd < r ? xcd * (q + 1) : r * (q + 1) + (xcd - r) * q) + off; }
;         const int nig = WGM * nN, gid = wgid / nig, fm = gid * WGM, gsz = (nM - fm) < WGM ? (nM - fm) : WGM;
;         u.pm = fm + ((wgid % nig) % gsz); u.pn = (wgid % nig) / gsz; return true;
.LBB0_170:
	v_readfirstlane_b32 s20, v208
	s_nop 3
	s_bitcmp1_b32 s20, 8
	s_cbranch_scc0 .Lgprio_3
	s_setprio 1
.Lgprio_3:
	s_cmpk_lt_i32 s51, 0x100
	s_mov_b64 s[14:15], -1
	s_cbranch_scc1 .LBB0_173
	s_and_b32 s4, s51, 0x7fffff00
	s_cmpk_eq_i32 s4, 0x100
	v_readlane_b32 s16, v249, 57
	s_cselect_b64 s[4:5], -1, 0
	v_readlane_b32 s17, v249, 58
	s_and_b64 s[4:5], s[16:17], s[4:5]
	s_mov_b64 s[14:15], 0
	s_andn2_b64 vcc, exec, s[4:5]
	s_mov_b64 s[4:5], 0
	s_cbranch_vccnz .LBB0_173
	s_and_b32 s4, s51, 0xff
	s_lshr_b32 s4, s4, s72
	s_and_b32 s26, s4, 7
	s_lshr_b32 s4, s4, 3
	s_or_b32 s4, s4, 32
	s_and_b32 s36, s73, s51
	s_and_b32 s28, s4, 63
	s_mov_b64 s[4:5], -1

;     __device__ bool next(int i, Unit& u) const {
;         const long L = (long)i * G + c;
;         if (L >= nwg) { const long j = L - nwg; if (j >= (long)nM2 * nN * nsplit) return false;
;             const int jj = (int)j; u.ks = jj % nsplit; const int tl = jj / nsplit; u.pn = tl % nN; u.pm = nM + tl / nN; return true; }
;         u.ks = -1;
;         int wgid = (int)L; { const int q = nwg / NXCD, r = nwg % NXCD, xcd = wgid % NXCD, off = wgid / NXCD; wgid = (xcd < r ? xcd * (q + 1) : r * (q + 1) + (xcd - r) * q) + off; }
;         const int nig = WGM * nN, gid = wgid / nig, fm = gid * WGM, gsz = (nM - fm) < WGM ? (nM - fm) : WGM;
;         u.pm = fm + ((wgid % nig) % gsz); u.pn = (wgid % nig) / gsz; return true;
.LBB0_231:
	v_readfirstlane_b32 s7, v208
	s_nop 3
	s_bitcmp1_b32 s7, 8
	s_cbranch_scc0 .Lgprio_4
	s_setprio 1
.Lgprio_4:
	s_cmp_lt_i32 s51, s6
	s_mul_i32 s5, s61, s61
	s_cbranch_scc1 .LBB0_234
	s_sub_u32 s14, s51, s6
	s_subb_u32 s15, 0, 0
	s_lshl_b32 s0, s5, 3
	v_mov_b32_e32 v0, s0
	v_cmp_ge_i64_e32 vcc, s[14:15], v[0:1]
	s_mov_b64 s[0:1], 0
	s_and_b64 vcc, exec, vcc
	s_mov_b64 s[12:13], 0
	s_cbranch_vccnz .LBB0_234
	s_sext_i32_i8 s4, s61
	v_cvt_f32_i32_e32 v0, s4
	s_sext_i32_i8 s8, s14
	v_cvt_f32_i32_e32 v2, s8
	s_xor_b32 s4, s8, s4
	v_rcp_iflag_f32_e32 v3, v0
	s_ashr_i32 s4, s4, 30
	s_or_b32 s4, s4, 1
	v_mul_f32_e32 v3, v2, v3
	v_trunc_f32_e32 v3, v3
	v_fma_f32 v2, -v3, v0, v2
	v_cvt_i32_f32_e32 v3, v3
	v_cmp_ge_f32_e64 s[8:9], |v2|, |v0|
	s_and_b64 s[8:9], s[8:9], exec
	s_cselect_b32 s4, s4, 0
	v_readfirstlane_b32 s8, v3
	s_add_i32 s8, s8, s4
	s_bfe_i32 s9, s8, 0x80000
	s_bfe_u32 s9, s9, 0x3000c
	s_add_i32 s9, s8, s9
	s_bfe_i32 s12, s9, 0x80000
	s_and_b32 s9, s9, 0xf8
	s_mul_i32 s4, s8, s61
	s_sext_i32_i16 s12, s12
	s_sub_i32 s8, s8, s9
	s_sub_i32 s4, s14, s4
	s_sext_i32_i8 s30, s8
	s_ashr_i32 s8, s12, 3
	s_sext_i32_i8 s4, s4
	s_add_i32 s92, s60, s8
	s_mov_b64 s[12:13], -1

; #define LAS __attribute__((address_space(3)))
;     __device__ bool next(int i, Unit& u) const {
;         const long L = (long)i * G + c;
;         if (L >= nwg) { const long j = L - nwg; if (j >= (long)nM2 * nN * nsplit) return false;
;             const int jj = (int)j; u.ks = jj % nsplit; const int tl = jj / nsplit; u.pn = tl % nN; u.pm = nM + tl / nN; return true; }
;         u.ks = -1;
;         int wgid = (int)L; { const int q = nwg / NXCD, r = nwg % NXCD, xcd = wgid % NXCD, off = wgid / NXCD; wgid = (xcd < r ? xcd * (q + 1) : r * (q + 1) + (xcd - r) * q) + off; }
;         const int nig = WGM * nN, gid = wgid / nig, fm = gid * WGM, gsz = (nM - fm) < WGM ? (nM - fm) : WGM;
;         u.pm = fm + ((wgid % nig) % gsz); u.pn = (wgid % nig) / gsz; return true;
; DI const float* ARGP(const Ctx& C, int i) {
;     volatile LAS unsigned* p = (volatile LAS unsigned*)(C.lds + ARG_OFF) + 2 * i;
;     const unsigned lo = __builtin_amdgcn_readfirstlane(p[0]), hi = __builtin_amdgcn_readfirstlane(p[1]);
;     return (const float*)(((unsigned long long)hi << 32) | (unsigned long long)lo);
; }
.LBB0_649:
	v_readlane_b32 s0, v248, 3
	s_cmp_gt_i32 s0, 0
	s_mov_b64 s[0:1], -1
	s_cbranch_scc0 .LBB0_680
	v_readlane_b32 s0, v249, 24
	v_readfirstlane_b32 s8, v208
	s_nop 3
	s_bitcmp1_b32 s8, 8
	s_cbranch_scc0 .Lgprio_5
	s_setprio 1
.Lgprio_5:
	s_cmpk_gt_i32 s51, 0x6e3
	v_mov_b32_e32 v0, s0
	ds_read_b32 v0, v0
	v_readlane_b32 s0, v249, 25
	s_waitcnt lgkmcnt(0)
	v_readfirstlane_b32 s6, v0
	v_mov_b32_e32 v0, s0
	ds_read_b32 v0, v0
	s_waitcnt lgkmcnt(0)
	v_readfirstlane_b32 s7, v0
	s_cbranch_scc1 .LBB0_679
	s_ashr_i32 s26, s51, 31
	s_lshr_b32 s0, s26, 29
	s_add_i32 s5, s51, s0
	s_and_b32 s0, s5, -8
	s_sub_i32 s9, s51, s0
	s_cmp_gt_i32 s9, 3
	s_mov_b64 s[0:1], -1
	s_cbranch_scc0 .LBB0_653
	s_mul_i32 s0, s9, 0xdc
	s_add_i32 s4, s0, 4
	s_mov_b64 s[0:1], 0
